# v7 + GLA chunk unit: v-tile and z_a loads issued together instead of one full drain per load
# baseline (speedup 1.0000x reference)
.LBB0_389:
	v_mov_b32_e32 v0, v1
	s_ashr_i32 s66, s21, 2
	v_mbcnt_lo_u32_b32 v0, -1, v0
	v_mbcnt_hi_u32_b32 v0, -1, v0
	v_add_u32_e32 v10, s54, v0
	s_ashr_i32 s67, s66, 31
	v_ashrrev_i32_e32 v6, 5, v10
	s_lshl_b64 s[6:7], s[66:67], 6
	v_ashrrev_i32_e32 v7, 31, v6
	v_lshl_add_u64 v[2:3], s[6:7], 0, v[6:7]
	s_and_b32 s0, s21, 3
	v_lshlrev_b64 v[2:3], 13, v[2:3]
	v_and_b32_e32 v16, 31, v10
	v_lshl_add_u64 v[2:3], s[18:19], 0, v[2:3]
	s_lshl_b32 s8, s0, 9
	s_mov_b32 s9, s87
	v_lshlrev_b32_e32 v0, 4, v16
	v_lshl_add_u64 v[2:3], v[2:3], 0, s[8:9]
	v_lshl_add_u64 v[2:3], v[2:3], 0, v[0:1]
	global_load_dwordx4 v[86:89], v[2:3], off offset:3712
	v_add_u32_e32 v8, 0, v0
	v_lshl_add_u32 v102, v6, 9, v8
	v_add_u32_e32 v9, 0x200, v10
	v_and_b32_e32 v11, 0x7f, v10
	s_lshl_b32 s86, s0, 8
	s_movk_i32 s0, 0x5000
	v_ashrrev_i32_e32 v17, 7, v10
	v_lshl_add_u32 v25, v17, 10, 0
	v_mov_b32_e32 v44, 0x41b17218
	v_ashrrev_i32_e32 v6, 5, v9
	v_ashrrev_i32_e32 v7, 31, v6
	v_lshl_add_u64 v[2:3], s[6:7], 0, v[6:7]
	v_lshlrev_b64 v[2:3], 13, v[2:3]
	v_lshl_add_u64 v[2:3], s[18:19], 0, v[2:3]
	v_lshl_add_u64 v[2:3], v[2:3], 0, s[8:9]
	v_lshl_add_u64 v[2:3], v[2:3], 0, v[0:1]
	global_load_dwordx4 v[90:93], v[2:3], off offset:3712
	v_lshl_add_u32 v103, v6, 9, v8
	v_add_u32_e32 v2, 0x400, v10
	v_ashrrev_i32_e32 v6, 5, v2
	v_ashrrev_i32_e32 v7, 31, v6
	v_lshl_add_u64 v[2:3], s[6:7], 0, v[6:7]
	v_lshlrev_b64 v[2:3], 13, v[2:3]
	v_lshl_add_u64 v[2:3], s[18:19], 0, v[2:3]
	v_lshl_add_u64 v[2:3], v[2:3], 0, s[8:9]
	v_lshl_add_u64 v[2:3], v[2:3], 0, v[0:1]
	global_load_dwordx4 v[94:97], v[2:3], off offset:3712
	v_lshl_add_u32 v104, v6, 9, v8
	v_add_u32_e32 v2, 0x600, v10
	v_ashrrev_i32_e32 v6, 5, v2
	v_ashrrev_i32_e32 v7, 31, v6
	v_lshl_add_u64 v[2:3], s[6:7], 0, v[6:7]
	v_lshlrev_b64 v[2:3], 13, v[2:3]
	v_lshl_add_u64 v[2:3], s[18:19], 0, v[2:3]
	v_lshl_add_u64 v[2:3], v[2:3], 0, s[8:9]
	v_lshl_add_u64 v[2:3], v[2:3], 0, v[0:1]
	global_load_dwordx4 v[98:101], v[2:3], off offset:3712
	v_lshl_add_u32 v105, v6, 9, v8
	v_lshl_add_u32 v6, v10, 2, 0
	v_lshlrev_b32_e32 v7, 2, v11
	v_readfirstlane_b32 s9, v10
	v_ashrrev_i32_e32 v4, 4, v10
	v_and_b32_e32 v0, 15, v10
	v_ashrrev_i32_e32 v5, 31, v4
	v_lshlrev_b32_e32 v0, 1, v0
	v_lshl_add_u64 v[4:5], s[6:7], 0, v[4:5]
	v_lshl_add_u64 v[2:3], s[18:19], 0, v[0:1]
	v_lshlrev_b64 v[4:5], 13, v[4:5]
	v_lshl_add_u64 v[4:5], v[2:3], 0, v[4:5]
	v_add_co_u32_e32 v4, vcc, s91, v4
	s_nop 1
	v_addc_co_u32_e32 v5, vcc, 0, v5, vcc
	global_load_ushort v106, v[4:5], off offset:1664
	v_ashrrev_i32_e32 v4, 4, v9
	v_ashrrev_i32_e32 v5, 31, v4
	v_lshl_add_u64 v[4:5], s[6:7], 0, v[4:5]
	v_lshlrev_b64 v[4:5], 13, v[4:5]
	v_lshl_add_u64 v[2:3], v[2:3], 0, v[4:5]
	v_add_co_u32_e32 v2, vcc, s91, v2
	s_nop 1
	v_addc_co_u32_e32 v3, vcc, 0, v3, vcc
	global_load_ushort v107, v[2:3], off offset:1664
	s_waitcnt vmcnt(5)
	ds_write_b128 v102, v[86:89]
	s_waitcnt vmcnt(4)
	ds_write_b128 v103, v[90:93]
	s_waitcnt vmcnt(3)
	ds_write_b128 v104, v[94:97]
	s_waitcnt vmcnt(2)
	ds_write_b128 v105, v[98:101]
	s_waitcnt vmcnt(0)
	v_lshlrev_b32_e32 v106, 16, v106
	v_lshlrev_b32_e32 v107, 16, v107
	ds_write2st64_b32 v6, v106, v107 offset0:208 offset1:216
	v_or_b32_e32 v0, s8, v7
	v_lshl_add_u64 v[4:5], s[14:15], 0, v[0:1]
	v_add_co_u32_e32 v2, vcc, s91, v4
	s_waitcnt lgkmcnt(0)
	s_nop 0
	v_addc_co_u32_e32 v3, vcc, 0, v5, vcc
	v_add_co_u32_e32 v8, vcc, s37, v4
	s_barrier
	s_nop 0
	v_addc_co_u32_e32 v9, vcc, 0, v5, vcc
	global_load_dword v18, v0, s[14:15]
	global_load_dword v19, v0, s[14:15] offset:2048
	global_load_dword v20, v[8:9], off offset:-4096
	global_load_dword v21, v[2:3], off offset:2048
	global_load_dword v12, v[8:9], off
	global_load_dword v13, v[8:9], off offset:2048
	v_add_co_u32_e32 v2, vcc, s56, v4
	s_mov_b32 s8, 0xbfb8aa3b
	s_nop 0
	v_addc_co_u32_e32 v3, vcc, 0, v5, vcc
	v_add_co_u32_e32 v22, vcc, s79, v4
	s_nop 1
	v_addc_co_u32_e32 v23, vcc, 0, v5, vcc
	global_load_dword v14, v[22:23], off offset:-4096
	global_load_dword v15, v[2:3], off offset:2048
	global_load_dword v8, v[22:23], off
	global_load_dword v9, v[22:23], off offset:2048
	v_add_co_u32_e32 v2, vcc, s0, v4
	s_movk_i32 s0, 0x7000
	s_nop 0
	v_addc_co_u32_e32 v3, vcc, 0, v5, vcc
	v_add_co_u32_e32 v26, vcc, s57, v4
	s_nop 1
	v_addc_co_u32_e32 v27, vcc, 0, v5, vcc
	global_load_dword v23, v[26:27], off offset:-4096
	global_load_dword v24, v[2:3], off offset:2048
	s_nop 0
	global_load_dword v2, v[26:27], off
	global_load_dword v3, v[26:27], off offset:2048
	v_add_co_u32_e32 v26, vcc, s0, v4
	s_mov_b32 s0, 0x3d800000
	s_nop 0
	v_addc_co_u32_e32 v27, vcc, 0, v5, vcc
	global_load_dword v4, v[26:27], off
	global_load_dword v5, v[26:27], off offset:2048
	s_nop 0
	global_load_dword v0, v0, s[16:17]
	ds_read_b128 v[26:29], v25 offset:53248
	ds_read_b128 v[30:33], v25 offset:53264
	ds_read_b128 v[34:37], v25 offset:53280
	ds_read_b128 v[38:41], v25 offset:53296
	s_waitcnt vmcnt(0) lgkmcnt(3)
	v_fma_f32 v22, v18, v26, v0
	v_fmac_f32_e32 v22, v19, v27
	v_fmac_f32_e32 v22, v20, v28
	v_fmac_f32_e32 v22, v21, v29
	s_waitcnt lgkmcnt(2)
	v_fmac_f32_e32 v22, v12, v30
	v_fmac_f32_e32 v22, v13, v31
	v_fmac_f32_e32 v22, v14, v32
	v_fmac_f32_e32 v22, v15, v33
	s_waitcnt lgkmcnt(1)
	v_fmac_f32_e32 v22, v8, v34
	v_fmac_f32_e32 v22, v9, v35
	v_fmac_f32_e32 v22, v23, v36
	v_fmac_f32_e32 v22, v24, v37
	s_waitcnt lgkmcnt(0)
	v_pk_mul_f32 v[26:27], v[2:3], v[38:39]
	s_nop 0
	v_add_f32_e32 v22, v22, v26
	v_add_f32_e32 v22, v22, v27
	v_pk_mul_f32 v[26:27], v[4:5], v[40:41]
	s_nop 0
	v_add_f32_e32 v22, v22, v26
	v_add_f32_e32 v22, v22, v27
	v_min_f32_e32 v26, 0, v22
	v_mul_f32_e64 v22, |v22|, s8
	v_exp_f32_e32 v22, v22
	s_nop 0
	v_add_f32_e32 v22, 1.0, v22
	v_cmp_gt_f32_e32 vcc, s5, v22
	s_nop 1
	v_cndmask_b32_e64 v27, 0, 32, vcc
	v_ldexp_f32 v22, v22, v27
	v_log_f32_e32 v22, v22
	s_nop 0
	v_mul_f32_e32 v27, 0x3f317217, v22
	v_fma_f32 v27, v22, s51, -v27
	v_fmac_f32_e32 v27, 0x3377d1cf, v22
	v_fmac_f32_e32 v27, 0x3f317217, v22
	v_cmp_lt_f32_e64 s[12:13], |v22|, s53
	s_nop 1
	v_cndmask_b32_e64 v22, v22, v27, s[12:13]
	v_cndmask_b32_e32 v27, 0, v44, vcc
	v_sub_f32_e32 v22, v22, v27
	v_sub_f32_e32 v22, v26, v22
	ds_read_b128 v[26:29], v25 offset:53312
	v_fma_f32 v22, v22, s0, 0
	s_mov_b32 s0, 0x8000
	s_waitcnt lgkmcnt(0)
	v_fma_f32 v30, v18, v26, v0
	v_fmac_f32_e32 v30, v19, v27
	v_fmac_f32_e32 v30, v20, v28
	v_fmac_f32_e32 v30, v21, v29
	ds_read_b128 v[26:29], v25 offset:53328
	s_waitcnt lgkmcnt(0)
	v_fmac_f32_e32 v30, v12, v26
	v_fmac_f32_e32 v30, v13, v27
	v_fmac_f32_e32 v30, v14, v28
	v_fmac_f32_e32 v30, v15, v29
	ds_read_b128 v[26:29], v25 offset:53344
	s_waitcnt lgkmcnt(0)
	v_fmac_f32_e32 v30, v8, v26
	v_fmac_f32_e32 v30, v9, v27
	v_fmac_f32_e32 v30, v23, v28
	v_fmac_f32_e32 v30, v24, v29
	ds_read_b128 v[26:29], v25 offset:53360
	s_waitcnt lgkmcnt(0)
	v_pk_mul_f32 v[26:27], v[2:3], v[26:27]
	s_nop 0
	v_add_f32_e32 v26, v30, v26
	v_add_f32_e32 v30, v26, v27
	v_pk_mul_f32 v[26:27], v[4:5], v[28:29]
	s_nop 0
	v_add_f32_e32 v26, v30, v26
	v_add_f32_e32 v26, v26, v27
	v_min_f32_e32 v27, 0, v26
	v_mul_f32_e64 v26, |v26|, s8
	v_exp_f32_e32 v26, v26
	s_nop 0
	v_add_f32_e32 v26, 1.0, v26
	v_cmp_gt_f32_e32 vcc, s5, v26
	s_nop 1
	v_cndmask_b32_e64 v28, 0, 32, vcc
	v_ldexp_f32 v26, v26, v28
	v_log_f32_e32 v26, v26
	s_nop 0
	v_mul_f32_e32 v28, 0x3f317217, v26
	v_fma_f32 v28, v26, s51, -v28
	v_fmac_f32_e32 v28, 0x3377d1cf, v26
	v_fmac_f32_e32 v28, 0x3f317217, v26
	v_cmp_lt_f32_e64 s[12:13], |v26|, s53
	s_nop 1
	v_cndmask_b32_e64 v26, v26, v28, s[12:13]
	v_cndmask_b32_e32 v28, 0, v44, vcc
	v_sub_f32_e32 v26, v26, v28
	ds_read_b128 v[28:31], v25 offset:53376
	v_sub_f32_e32 v26, v27, v26
	v_fmamk_f32 v26, v26, 0x3d800000, v22
	s_waitcnt lgkmcnt(0)
	v_fma_f32 v27, v18, v28, v0
	v_fmac_f32_e32 v27, v19, v29
	v_fmac_f32_e32 v27, v20, v30
	v_fmac_f32_e32 v27, v21, v31
	ds_read_b128 v[28:31], v25 offset:53392
	s_waitcnt lgkmcnt(0)
	v_fmac_f32_e32 v27, v12, v28
	v_fmac_f32_e32 v27, v13, v29
	v_fmac_f32_e32 v27, v14, v30
	v_fmac_f32_e32 v27, v15, v31
	ds_read_b128 v[28:31], v25 offset:53408
	s_waitcnt lgkmcnt(0)
	v_fmac_f32_e32 v27, v8, v28
	v_fmac_f32_e32 v27, v9, v29
	v_fmac_f32_e32 v27, v23, v30
	v_fmac_f32_e32 v27, v24, v31
	ds_read_b128 v[28:31], v25 offset:53424
	s_waitcnt lgkmcnt(0)
	v_pk_mul_f32 v[28:29], v[2:3], v[28:29]
	s_nop 0
	v_add_f32_e32 v27, v27, v28
	v_add_f32_e32 v27, v27, v29
	v_pk_mul_f32 v[28:29], v[4:5], v[30:31]
	s_nop 0
	v_add_f32_e32 v27, v27, v28
	v_add_f32_e32 v27, v27, v29
	v_min_f32_e32 v28, 0, v27
	v_mul_f32_e64 v27, |v27|, s8
	v_exp_f32_e32 v27, v27
	s_nop 0
	v_add_f32_e32 v27, 1.0, v27
	v_cmp_gt_f32_e32 vcc, s5, v27
	s_nop 1
	v_cndmask_b32_e64 v29, 0, 32, vcc
	v_ldexp_f32 v27, v27, v29
	v_log_f32_e32 v27, v27
	s_nop 0
	v_mul_f32_e32 v29, 0x3f317217, v27
	v_fma_f32 v29, v27, s51, -v29
	v_fmac_f32_e32 v29, 0x3377d1cf, v27
	v_fmac_f32_e32 v29, 0x3f317217, v27
	v_cmp_lt_f32_e64 s[12:13], |v27|, s53
	s_nop 1
	v_cndmask_b32_e64 v27, v27, v29, s[12:13]
	v_cndmask_b32_e32 v29, 0, v44, vcc
	v_sub_f32_e32 v27, v27, v29
	v_sub_f32_e32 v27, v28, v27
	ds_read_b128 v[28:31], v25 offset:53440
	v_fmamk_f32 v27, v27, 0x3d800000, v26
	s_waitcnt lgkmcnt(0)
	v_fma_f32 v32, v18, v28, v0
	v_fmac_f32_e32 v32, v19, v29
	v_fmac_f32_e32 v32, v20, v30
	v_fmac_f32_e32 v32, v21, v31
	ds_read_b128 v[28:31], v25 offset:53456
	s_waitcnt lgkmcnt(0)
	v_fmac_f32_e32 v32, v12, v28
	v_fmac_f32_e32 v32, v13, v29
	v_fmac_f32_e32 v32, v14, v30
	v_fmac_f32_e32 v32, v15, v31
	ds_read_b128 v[28:31], v25 offset:53472
	s_waitcnt lgkmcnt(0)
	v_fmac_f32_e32 v32, v8, v28
	v_fmac_f32_e32 v32, v9, v29
	v_fmac_f32_e32 v32, v23, v30
	v_fmac_f32_e32 v32, v24, v31
	ds_read_b128 v[28:31], v25 offset:53488
	s_waitcnt lgkmcnt(0)
	v_pk_mul_f32 v[28:29], v[2:3], v[28:29]
	s_nop 0
	v_add_f32_e32 v28, v32, v28
	v_add_f32_e32 v32, v28, v29
	v_pk_mul_f32 v[28:29], v[4:5], v[30:31]
	s_nop 0
	v_add_f32_e32 v28, v32, v28
	v_add_f32_e32 v28, v28, v29
	v_min_f32_e32 v29, 0, v28
	v_mul_f32_e64 v28, |v28|, s8
	v_exp_f32_e32 v28, v28
	s_nop 0
	v_add_f32_e32 v28, 1.0, v28
	v_cmp_gt_f32_e32 vcc, s5, v28
	s_nop 1
	v_cndmask_b32_e64 v30, 0, 32, vcc
	v_ldexp_f32 v28, v28, v30
	v_log_f32_e32 v28, v28
	s_nop 0
	v_mul_f32_e32 v30, 0x3f317217, v28
	v_fma_f32 v30, v28, s51, -v30
	v_fmac_f32_e32 v30, 0x3377d1cf, v28
	v_fmac_f32_e32 v30, 0x3f317217, v28
	v_cmp_lt_f32_e64 s[12:13], |v28|, s53
	s_nop 1
	v_cndmask_b32_e64 v28, v28, v30, s[12:13]
	v_cndmask_b32_e32 v30, 0, v44, vcc
	v_sub_f32_e32 v28, v28, v30
	ds_read_b128 v[30:33], v25 offset:53504
	v_sub_f32_e32 v28, v29, v28
	v_fmamk_f32 v28, v28, 0x3d800000, v27
	s_waitcnt lgkmcnt(0)
	v_fma_f32 v29, v18, v30, v0
	v_fmac_f32_e32 v29, v19, v31
	v_fmac_f32_e32 v29, v20, v32
	v_fmac_f32_e32 v29, v21, v33
	ds_read_b128 v[30:33], v25 offset:53520
	s_waitcnt lgkmcnt(0)
	v_fmac_f32_e32 v29, v12, v30
	v_fmac_f32_e32 v29, v13, v31
	v_fmac_f32_e32 v29, v14, v32
	v_fmac_f32_e32 v29, v15, v33
	ds_read_b128 v[30:33], v25 offset:53536
	s_waitcnt lgkmcnt(0)
	v_fmac_f32_e32 v29, v8, v30
	v_fmac_f32_e32 v29, v9, v31
	v_fmac_f32_e32 v29, v23, v32
	v_fmac_f32_e32 v29, v24, v33
	ds_read_b128 v[30:33], v25 offset:53552
	s_waitcnt lgkmcnt(0)
	v_pk_mul_f32 v[30:31], v[2:3], v[30:31]
	s_nop 0
	v_add_f32_e32 v29, v29, v30
	v_add_f32_e32 v29, v29, v31
	v_pk_mul_f32 v[30:31], v[4:5], v[32:33]
	s_nop 0
	v_add_f32_e32 v29, v29, v30
	v_add_f32_e32 v29, v29, v31
	v_min_f32_e32 v30, 0, v29
	v_mul_f32_e64 v29, |v29|, s8
	v_exp_f32_e32 v29, v29
	s_nop 0
	v_add_f32_e32 v29, 1.0, v29
	v_cmp_gt_f32_e32 vcc, s5, v29
	s_nop 1
	v_cndmask_b32_e64 v31, 0, 32, vcc
	v_ldexp_f32 v29, v29, v31
	v_log_f32_e32 v29, v29
	s_nop 0
	v_mul_f32_e32 v31, 0x3f317217, v29
	v_fma_f32 v31, v29, s51, -v31
	v_fmac_f32_e32 v31, 0x3377d1cf, v29
	v_fmac_f32_e32 v31, 0x3f317217, v29
	v_cmp_lt_f32_e64 s[12:13], |v29|, s53
	s_nop 1
	v_cndmask_b32_e64 v29, v29, v31, s[12:13]
	v_cndmask_b32_e32 v31, 0, v44, vcc
	v_sub_f32_e32 v29, v29, v31
	v_sub_f32_e32 v29, v30, v29
	ds_read_b128 v[30:33], v25 offset:53568
	v_fmamk_f32 v29, v29, 0x3d800000, v28
	s_waitcnt lgkmcnt(0)
	v_fma_f32 v34, v18, v30, v0
	v_fmac_f32_e32 v34, v19, v31
	v_fmac_f32_e32 v34, v20, v32
	v_fmac_f32_e32 v34, v21, v33
	ds_read_b128 v[30:33], v25 offset:53584
	s_waitcnt lgkmcnt(0)
	v_fmac_f32_e32 v34, v12, v30
	v_fmac_f32_e32 v34, v13, v31
	v_fmac_f32_e32 v34, v14, v32
	v_fmac_f32_e32 v34, v15, v33
	ds_read_b128 v[30:33], v25 offset:53600
	s_waitcnt lgkmcnt(0)
	v_fmac_f32_e32 v34, v8, v30
	v_fmac_f32_e32 v34, v9, v31
	v_fmac_f32_e32 v34, v23, v32
	v_fmac_f32_e32 v34, v24, v33
	ds_read_b128 v[30:33], v25 offset:53616
	s_waitcnt lgkmcnt(0)
	v_pk_mul_f32 v[30:31], v[2:3], v[30:31]
	s_nop 0
	v_add_f32_e32 v30, v34, v30
	v_add_f32_e32 v34, v30, v31
	v_pk_mul_f32 v[30:31], v[4:5], v[32:33]
	s_nop 0
	v_add_f32_e32 v30, v34, v30
	v_add_f32_e32 v30, v30, v31
	v_min_f32_e32 v31, 0, v30
	v_mul_f32_e64 v30, |v30|, s8
	v_exp_f32_e32 v30, v30
	s_nop 0
	v_add_f32_e32 v30, 1.0, v30
	v_cmp_gt_f32_e32 vcc, s5, v30
	s_nop 1
	v_cndmask_b32_e64 v32, 0, 32, vcc
	v_ldexp_f32 v30, v30, v32
	v_log_f32_e32 v30, v30
	s_nop 0
	v_mul_f32_e32 v32, 0x3f317217, v30
	v_fma_f32 v32, v30, s51, -v32
	v_fmac_f32_e32 v32, 0x3377d1cf, v30
	v_fmac_f32_e32 v32, 0x3f317217, v30
	v_cmp_lt_f32_e64 s[12:13], |v30|, s53
	s_nop 1
	v_cndmask_b32_e64 v30, v30, v32, s[12:13]
	v_cndmask_b32_e32 v32, 0, v44, vcc
	v_sub_f32_e32 v30, v30, v32
	ds_read_b128 v[32:35], v25 offset:53632
	v_sub_f32_e32 v30, v31, v30
	v_fmamk_f32 v30, v30, 0x3d800000, v29
	s_waitcnt lgkmcnt(0)
	v_fma_f32 v31, v18, v32, v0
	v_fmac_f32_e32 v31, v19, v33
	v_fmac_f32_e32 v31, v20, v34
	v_fmac_f32_e32 v31, v21, v35
	ds_read_b128 v[32:35], v25 offset:53648
	s_waitcnt lgkmcnt(0)
	v_fmac_f32_e32 v31, v12, v32
	v_fmac_f32_e32 v31, v13, v33
	v_fmac_f32_e32 v31, v14, v34
	v_fmac_f32_e32 v31, v15, v35
	ds_read_b128 v[32:35], v25 offset:53664
	s_waitcnt lgkmcnt(0)
	v_fmac_f32_e32 v31, v8, v32
	v_fmac_f32_e32 v31, v9, v33
	v_fmac_f32_e32 v31, v23, v34
	v_fmac_f32_e32 v31, v24, v35
	ds_read_b128 v[32:35], v25 offset:53680
	s_waitcnt lgkmcnt(0)
	v_pk_mul_f32 v[32:33], v[2:3], v[32:33]
	s_nop 0
	v_add_f32_e32 v31, v31, v32
	v_add_f32_e32 v31, v31, v33
	v_pk_mul_f32 v[32:33], v[4:5], v[34:35]
	s_nop 0
	v_add_f32_e32 v31, v31, v32
	v_add_f32_e32 v31, v31, v33
	v_min_f32_e32 v32, 0, v31
	v_mul_f32_e64 v31, |v31|, s8
	v_exp_f32_e32 v31, v31
	s_nop 0
	v_add_f32_e32 v31, 1.0, v31
	v_cmp_gt_f32_e32 vcc, s5, v31
	s_nop 1
	v_cndmask_b32_e64 v33, 0, 32, vcc
	v_ldexp_f32 v31, v31, v33
	v_log_f32_e32 v31, v31
	s_nop 0
	v_mul_f32_e32 v33, 0x3f317217, v31
	v_fma_f32 v33, v31, s51, -v33
	v_fmac_f32_e32 v33, 0x3377d1cf, v31
	v_fmac_f32_e32 v33, 0x3f317217, v31
	v_cmp_lt_f32_e64 s[12:13], |v31|, s53
	s_nop 1
	v_cndmask_b32_e64 v31, v31, v33, s[12:13]
	v_cndmask_b32_e32 v33, 0, v44, vcc
	v_sub_f32_e32 v31, v31, v33
	v_sub_f32_e32 v31, v32, v31
	ds_read_b128 v[32:35], v25 offset:53696
	v_fmamk_f32 v31, v31, 0x3d800000, v30
	s_waitcnt lgkmcnt(0)
	v_fma_f32 v36, v18, v32, v0
	v_fmac_f32_e32 v36, v19, v33
	v_fmac_f32_e32 v36, v20, v34
	v_fmac_f32_e32 v36, v21, v35
	ds_read_b128 v[32:35], v25 offset:53712
	s_waitcnt lgkmcnt(0)
	v_fmac_f32_e32 v36, v12, v32
	v_fmac_f32_e32 v36, v13, v33
	v_fmac_f32_e32 v36, v14, v34
	v_fmac_f32_e32 v36, v15, v35
	ds_read_b128 v[32:35], v25 offset:53728
	s_waitcnt lgkmcnt(0)
	v_fmac_f32_e32 v36, v8, v32
	v_fmac_f32_e32 v36, v9, v33
	v_fmac_f32_e32 v36, v23, v34
	v_fmac_f32_e32 v36, v24, v35
	ds_read_b128 v[32:35], v25 offset:53744
	s_waitcnt lgkmcnt(0)
	v_pk_mul_f32 v[32:33], v[2:3], v[32:33]
	s_nop 0
	v_add_f32_e32 v32, v36, v32
	v_add_f32_e32 v36, v32, v33
	v_pk_mul_f32 v[32:33], v[4:5], v[34:35]
	s_nop 0
	v_add_f32_e32 v32, v36, v32
	v_add_f32_e32 v32, v32, v33
	v_min_f32_e32 v33, 0, v32
	v_mul_f32_e64 v32, |v32|, s8
	v_exp_f32_e32 v32, v32
	s_nop 0
	v_add_f32_e32 v32, 1.0, v32
	v_cmp_gt_f32_e32 vcc, s5, v32
	s_nop 1
	v_cndmask_b32_e64 v34, 0, 32, vcc
	v_ldexp_f32 v32, v32, v34
	v_log_f32_e32 v32, v32
	s_nop 0
	v_mul_f32_e32 v34, 0x3f317217, v32
	v_fma_f32 v34, v32, s51, -v34
	v_fmac_f32_e32 v34, 0x3377d1cf, v32
	v_fmac_f32_e32 v34, 0x3f317217, v32
	v_cmp_lt_f32_e64 s[12:13], |v32|, s53
	s_nop 1
	v_cndmask_b32_e64 v32, v32, v34, s[12:13]
	v_cndmask_b32_e32 v34, 0, v44, vcc
	v_sub_f32_e32 v32, v32, v34
	ds_read_b128 v[34:37], v25 offset:53760
	v_sub_f32_e32 v32, v33, v32
	v_fmamk_f32 v32, v32, 0x3d800000, v31
	s_waitcnt lgkmcnt(0)
	v_fma_f32 v33, v18, v34, v0
	v_fmac_f32_e32 v33, v19, v35
	v_fmac_f32_e32 v33, v20, v36
	v_fmac_f32_e32 v33, v21, v37
	ds_read_b128 v[34:37], v25 offset:53776
	s_waitcnt lgkmcnt(0)
	v_fmac_f32_e32 v33, v12, v34
	v_fmac_f32_e32 v33, v13, v35
	v_fmac_f32_e32 v33, v14, v36
	v_fmac_f32_e32 v33, v15, v37
	ds_read_b128 v[34:37], v25 offset:53792
	s_waitcnt lgkmcnt(0)
	v_fmac_f32_e32 v33, v8, v34
	v_fmac_f32_e32 v33, v9, v35
	v_fmac_f32_e32 v33, v23, v36
	v_fmac_f32_e32 v33, v24, v37
	ds_read_b128 v[34:37], v25 offset:53808
	s_waitcnt lgkmcnt(0)
	v_pk_mul_f32 v[34:35], v[2:3], v[34:35]
	s_nop 0
	v_add_f32_e32 v33, v33, v34
	v_add_f32_e32 v33, v33, v35
	v_pk_mul_f32 v[34:35], v[4:5], v[36:37]
	s_nop 0
	v_add_f32_e32 v33, v33, v34
	v_add_f32_e32 v33, v33, v35
	v_min_f32_e32 v34, 0, v33
	v_mul_f32_e64 v33, |v33|, s8
	v_exp_f32_e32 v33, v33
	s_nop 0
	v_add_f32_e32 v33, 1.0, v33
	v_cmp_gt_f32_e32 vcc, s5, v33
	s_nop 1
	v_cndmask_b32_e64 v35, 0, 32, vcc
	v_ldexp_f32 v33, v33, v35
	v_log_f32_e32 v33, v33
	s_nop 0
	v_mul_f32_e32 v35, 0x3f317217, v33
	v_fma_f32 v35, v33, s51, -v35
	v_fmac_f32_e32 v35, 0x3377d1cf, v33
	v_fmac_f32_e32 v35, 0x3f317217, v33
	v_cmp_lt_f32_e64 s[12:13], |v33|, s53
	s_nop 1
	v_cndmask_b32_e64 v33, v33, v35, s[12:13]
	v_cndmask_b32_e32 v35, 0, v44, vcc
	v_sub_f32_e32 v33, v33, v35
	v_sub_f32_e32 v33, v34, v33
	ds_read_b128 v[34:37], v25 offset:53824
	v_fmamk_f32 v33, v33, 0x3d800000, v32
	s_waitcnt lgkmcnt(0)
	v_fma_f32 v38, v18, v34, v0
	v_fmac_f32_e32 v38, v19, v35
	v_fmac_f32_e32 v38, v20, v36
	v_fmac_f32_e32 v38, v21, v37
	ds_read_b128 v[34:37], v25 offset:53840
	s_waitcnt lgkmcnt(0)
	v_fmac_f32_e32 v38, v12, v34
	v_fmac_f32_e32 v38, v13, v35
	v_fmac_f32_e32 v38, v14, v36
	v_fmac_f32_e32 v38, v15, v37
	ds_read_b128 v[34:37], v25 offset:53856
	s_waitcnt lgkmcnt(0)
	v_fmac_f32_e32 v38, v8, v34
	v_fmac_f32_e32 v38, v9, v35
	v_fmac_f32_e32 v38, v23, v36
	v_fmac_f32_e32 v38, v24, v37
	ds_read_b128 v[34:37], v25 offset:53872
	s_waitcnt lgkmcnt(0)
	v_pk_mul_f32 v[34:35], v[2:3], v[34:35]
	s_nop 0
	v_add_f32_e32 v34, v38, v34
	v_add_f32_e32 v38, v34, v35
	v_pk_mul_f32 v[34:35], v[4:5], v[36:37]
	s_nop 0
	v_add_f32_e32 v34, v38, v34
	v_add_f32_e32 v34, v34, v35
	v_min_f32_e32 v35, 0, v34
	v_mul_f32_e64 v34, |v34|, s8
	v_exp_f32_e32 v34, v34
	s_nop 0
	v_add_f32_e32 v34, 1.0, v34
	v_cmp_gt_f32_e32 vcc, s5, v34
	s_nop 1
	v_cndmask_b32_e64 v36, 0, 32, vcc
	v_ldexp_f32 v34, v34, v36
	v_log_f32_e32 v34, v34
	s_nop 0
	v_mul_f32_e32 v36, 0x3f317217, v34
	v_fma_f32 v36, v34, s51, -v36
	v_fmac_f32_e32 v36, 0x3377d1cf, v34
	v_fmac_f32_e32 v36, 0x3f317217, v34
	v_cmp_lt_f32_e64 s[12:13], |v34|, s53
	s_nop 1
	v_cndmask_b32_e64 v34, v34, v36, s[12:13]
	v_cndmask_b32_e32 v36, 0, v44, vcc
	v_sub_f32_e32 v34, v34, v36
	ds_read_b128 v[36:39], v25 offset:53888
	v_sub_f32_e32 v34, v35, v34
	v_fmamk_f32 v34, v34, 0x3d800000, v33
	s_waitcnt lgkmcnt(0)
	v_fma_f32 v35, v18, v36, v0
	v_fmac_f32_e32 v35, v19, v37
	v_fmac_f32_e32 v35, v20, v38
	v_fmac_f32_e32 v35, v21, v39
	ds_read_b128 v[36:39], v25 offset:53904
	s_waitcnt lgkmcnt(0)
	v_fmac_f32_e32 v35, v12, v36
	v_fmac_f32_e32 v35, v13, v37
	v_fmac_f32_e32 v35, v14, v38
	v_fmac_f32_e32 v35, v15, v39
	ds_read_b128 v[36:39], v25 offset:53920
	s_waitcnt lgkmcnt(0)
	v_fmac_f32_e32 v35, v8, v36
	v_fmac_f32_e32 v35, v9, v37
	v_fmac_f32_e32 v35, v23, v38
	v_fmac_f32_e32 v35, v24, v39
	ds_read_b128 v[36:39], v25 offset:53936
	s_waitcnt lgkmcnt(0)
	v_pk_mul_f32 v[36:37], v[2:3], v[36:37]
	s_nop 0
	v_add_f32_e32 v35, v35, v36
	v_add_f32_e32 v35, v35, v37
	v_pk_mul_f32 v[36:37], v[4:5], v[38:39]
	s_nop 0
	v_add_f32_e32 v35, v35, v36
	v_add_f32_e32 v35, v35, v37
	v_min_f32_e32 v36, 0, v35
	v_mul_f32_e64 v35, |v35|, s8
	v_exp_f32_e32 v35, v35
	s_nop 0
	v_add_f32_e32 v35, 1.0, v35
	v_cmp_gt_f32_e32 vcc, s5, v35
	s_nop 1
	v_cndmask_b32_e64 v37, 0, 32, vcc
	v_ldexp_f32 v35, v35, v37
	v_log_f32_e32 v35, v35
	s_nop 0
	v_mul_f32_e32 v37, 0x3f317217, v35
	v_fma_f32 v37, v35, s51, -v37
	v_fmac_f32_e32 v37, 0x3377d1cf, v35
	v_fmac_f32_e32 v37, 0x3f317217, v35
	v_cmp_lt_f32_e64 s[12:13], |v35|, s53
	s_nop 1
	v_cndmask_b32_e64 v35, v35, v37, s[12:13]
	v_cndmask_b32_e32 v37, 0, v44, vcc
	v_sub_f32_e32 v35, v35, v37
	v_sub_f32_e32 v35, v36, v35
	ds_read_b128 v[36:39], v25 offset:53952
	v_fmamk_f32 v35, v35, 0x3d800000, v34
	s_waitcnt lgkmcnt(0)
	v_fma_f32 v40, v18, v36, v0
	v_fmac_f32_e32 v40, v19, v37
	v_fmac_f32_e32 v40, v20, v38
	v_fmac_f32_e32 v40, v21, v39
	ds_read_b128 v[36:39], v25 offset:53968
	s_waitcnt lgkmcnt(0)
	v_fmac_f32_e32 v40, v12, v36
	v_fmac_f32_e32 v40, v13, v37
	v_fmac_f32_e32 v40, v14, v38
	v_fmac_f32_e32 v40, v15, v39
	ds_read_b128 v[36:39], v25 offset:53984
	s_waitcnt lgkmcnt(0)
	v_fmac_f32_e32 v40, v8, v36
	v_fmac_f32_e32 v40, v9, v37
	v_fmac_f32_e32 v40, v23, v38
	v_fmac_f32_e32 v40, v24, v39
	ds_read_b128 v[36:39], v25 offset:54000
	s_waitcnt lgkmcnt(0)
	v_pk_mul_f32 v[36:37], v[2:3], v[36:37]
	s_nop 0
	v_add_f32_e32 v36, v40, v36
	v_add_f32_e32 v40, v36, v37
	v_pk_mul_f32 v[36:37], v[4:5], v[38:39]
	s_nop 0
	v_add_f32_e32 v36, v40, v36
	v_add_f32_e32 v36, v36, v37
	v_min_f32_e32 v37, 0, v36
	v_mul_f32_e64 v36, |v36|, s8
	v_exp_f32_e32 v36, v36
	s_nop 0
	v_add_f32_e32 v36, 1.0, v36
	v_cmp_gt_f32_e32 vcc, s5, v36
	s_nop 1
	v_cndmask_b32_e64 v38, 0, 32, vcc
	v_ldexp_f32 v36, v36, v38
	v_log_f32_e32 v36, v36
	s_nop 0
	v_mul_f32_e32 v38, 0x3f317217, v36
	v_fma_f32 v38, v36, s51, -v38
	v_fmac_f32_e32 v38, 0x3377d1cf, v36
	v_fmac_f32_e32 v38, 0x3f317217, v36
	v_cmp_lt_f32_e64 s[12:13], |v36|, s53
	s_nop 1
	v_cndmask_b32_e64 v36, v36, v38, s[12:13]
	v_cndmask_b32_e32 v38, 0, v44, vcc
	v_sub_f32_e32 v36, v36, v38
	ds_read_b128 v[38:41], v25 offset:54016
	v_sub_f32_e32 v36, v37, v36
	v_fmamk_f32 v36, v36, 0x3d800000, v35
	s_waitcnt lgkmcnt(0)
	v_fma_f32 v37, v18, v38, v0
	v_fmac_f32_e32 v37, v19, v39
	v_fmac_f32_e32 v37, v20, v40
	v_fmac_f32_e32 v37, v21, v41
	ds_read_b128 v[38:41], v25 offset:54032
	s_waitcnt lgkmcnt(0)
	v_fmac_f32_e32 v37, v12, v38
	v_fmac_f32_e32 v37, v13, v39
	v_fmac_f32_e32 v37, v14, v40
	v_fmac_f32_e32 v37, v15, v41
	ds_read_b128 v[38:41], v25 offset:54048
	s_waitcnt lgkmcnt(0)
	v_fmac_f32_e32 v37, v8, v38
	v_fmac_f32_e32 v37, v9, v39
	v_fmac_f32_e32 v37, v23, v40
	v_fmac_f32_e32 v37, v24, v41
	ds_read_b128 v[38:41], v25 offset:54064
	s_waitcnt lgkmcnt(0)
	v_pk_mul_f32 v[38:39], v[2:3], v[38:39]
	s_nop 0
	v_add_f32_e32 v37, v37, v38
	v_add_f32_e32 v37, v37, v39
	v_pk_mul_f32 v[38:39], v[4:5], v[40:41]
	s_nop 0
	v_add_f32_e32 v37, v37, v38
	v_add_f32_e32 v37, v37, v39
	v_min_f32_e32 v38, 0, v37
	v_mul_f32_e64 v37, |v37|, s8
	v_exp_f32_e32 v37, v37
	s_nop 0
	v_add_f32_e32 v37, 1.0, v37
	v_cmp_gt_f32_e32 vcc, s5, v37
	s_nop 1
	v_cndmask_b32_e64 v39, 0, 32, vcc
	v_ldexp_f32 v37, v37, v39
	v_log_f32_e32 v37, v37
	s_nop 0
	v_mul_f32_e32 v39, 0x3f317217, v37
	v_fma_f32 v39, v37, s51, -v39
	v_fmac_f32_e32 v39, 0x3377d1cf, v37
	v_fmac_f32_e32 v39, 0x3f317217, v37
	v_cmp_lt_f32_e64 s[12:13], |v37|, s53
	s_nop 1
	v_cndmask_b32_e64 v37, v37, v39, s[12:13]
	v_cndmask_b32_e32 v39, 0, v44, vcc
	v_sub_f32_e32 v37, v37, v39
	v_sub_f32_e32 v37, v38, v37
	ds_read_b128 v[38:41], v25 offset:54080
	v_fmamk_f32 v37, v37, 0x3d800000, v36
	s_waitcnt lgkmcnt(0)
	v_fma_f32 v42, v18, v38, v0
	v_fmac_f32_e32 v42, v19, v39
	v_fmac_f32_e32 v42, v20, v40
	v_fmac_f32_e32 v42, v21, v41
	ds_read_b128 v[38:41], v25 offset:54096
	s_waitcnt lgkmcnt(0)
	v_fmac_f32_e32 v42, v12, v38
	v_fmac_f32_e32 v42, v13, v39
	v_fmac_f32_e32 v42, v14, v40
	v_fmac_f32_e32 v42, v15, v41
	ds_read_b128 v[38:41], v25 offset:54112
	s_waitcnt lgkmcnt(0)
	v_fmac_f32_e32 v42, v8, v38
	v_fmac_f32_e32 v42, v9, v39
	v_fmac_f32_e32 v42, v23, v40
	v_fmac_f32_e32 v42, v24, v41
	ds_read_b128 v[38:41], v25 offset:54128
	s_waitcnt lgkmcnt(0)
	v_pk_mul_f32 v[38:39], v[2:3], v[38:39]
	s_nop 0
	v_add_f32_e32 v38, v42, v38
	v_add_f32_e32 v42, v38, v39
	v_pk_mul_f32 v[38:39], v[4:5], v[40:41]
	s_nop 0
	v_add_f32_e32 v38, v42, v38
	v_add_f32_e32 v38, v38, v39
	v_min_f32_e32 v39, 0, v38
	v_mul_f32_e64 v38, |v38|, s8
	v_exp_f32_e32 v38, v38
	s_nop 0
	v_add_f32_e32 v38, 1.0, v38
	v_cmp_gt_f32_e32 vcc, s5, v38
	s_nop 1
	v_cndmask_b32_e64 v40, 0, 32, vcc
	v_ldexp_f32 v38, v38, v40
	v_log_f32_e32 v38, v38
	s_nop 0
	v_mul_f32_e32 v40, 0x3f317217, v38
	v_fma_f32 v40, v38, s51, -v40
	v_fmac_f32_e32 v40, 0x3377d1cf, v38
	v_fmac_f32_e32 v40, 0x3f317217, v38
	v_cmp_lt_f32_e64 s[12:13], |v38|, s53
	s_nop 1
	v_cndmask_b32_e64 v38, v38, v40, s[12:13]
	v_cndmask_b32_e32 v40, 0, v44, vcc
	v_sub_f32_e32 v38, v38, v40
	ds_read_b128 v[40:43], v25 offset:54144
	v_sub_f32_e32 v38, v39, v38
	v_fmamk_f32 v38, v38, 0x3d800000, v37
	s_waitcnt lgkmcnt(0)
	v_fma_f32 v39, v18, v40, v0
	v_fmac_f32_e32 v39, v19, v41
	v_fmac_f32_e32 v39, v20, v42
	v_fmac_f32_e32 v39, v21, v43
	ds_read_b128 v[40:43], v25 offset:54160
	s_waitcnt lgkmcnt(0)
	v_fmac_f32_e32 v39, v12, v40
	v_fmac_f32_e32 v39, v13, v41
	v_fmac_f32_e32 v39, v14, v42
	v_fmac_f32_e32 v39, v15, v43
	ds_read_b128 v[40:43], v25 offset:54176
	s_waitcnt lgkmcnt(0)
	v_fmac_f32_e32 v39, v8, v40
	v_fmac_f32_e32 v39, v9, v41
	v_fmac_f32_e32 v39, v23, v42
	v_fmac_f32_e32 v39, v24, v43
	ds_read_b128 v[40:43], v25 offset:54192
	s_waitcnt lgkmcnt(0)
	v_pk_mul_f32 v[40:41], v[2:3], v[40:41]
	s_nop 0
	v_add_f32_e32 v39, v39, v40
	v_add_f32_e32 v39, v39, v41
	v_pk_mul_f32 v[40:41], v[4:5], v[42:43]
	s_nop 0
	v_add_f32_e32 v39, v39, v40
	v_add_f32_e32 v39, v39, v41
	v_min_f32_e32 v40, 0, v39
	v_mul_f32_e64 v39, |v39|, s8
	v_exp_f32_e32 v39, v39
	s_nop 0
	v_add_f32_e32 v39, 1.0, v39
	v_cmp_gt_f32_e32 vcc, s5, v39
	s_nop 1
	v_cndmask_b32_e64 v41, 0, 32, vcc
	v_ldexp_f32 v39, v39, v41
	v_log_f32_e32 v39, v39
	s_nop 0
	v_mul_f32_e32 v41, 0x3f317217, v39
	v_fma_f32 v41, v39, s51, -v41
	v_fmac_f32_e32 v41, 0x3377d1cf, v39
	v_fmac_f32_e32 v41, 0x3f317217, v39
	v_cmp_lt_f32_e64 s[12:13], |v39|, s53
	s_nop 1
	v_cndmask_b32_e64 v39, v39, v41, s[12:13]
	v_cndmask_b32_e32 v41, 0, v44, vcc
	v_sub_f32_e32 v39, v39, v41
	v_sub_f32_e32 v39, v40, v39
	ds_read_b128 v[40:43], v25 offset:54208
	v_fmamk_f32 v39, v39, 0x3d800000, v38
	s_waitcnt lgkmcnt(0)
	v_fmac_f32_e32 v0, v18, v40
	v_fmac_f32_e32 v0, v19, v41
	v_fmac_f32_e32 v0, v20, v42
	v_fmac_f32_e32 v0, v21, v43
	ds_read_b128 v[18:21], v25 offset:54224
	s_waitcnt lgkmcnt(0)
	v_fmac_f32_e32 v0, v12, v18
	v_fmac_f32_e32 v0, v13, v19
	v_fmac_f32_e32 v0, v14, v20
	v_fmac_f32_e32 v0, v15, v21
	ds_read_b128 v[12:15], v25 offset:54240
	s_waitcnt lgkmcnt(0)
	v_fmac_f32_e32 v0, v8, v12
	v_fmac_f32_e32 v0, v9, v13
	v_fmac_f32_e32 v0, v23, v14
	v_fmac_f32_e32 v0, v24, v15
	ds_read_b128 v[12:15], v25 offset:54256
	s_waitcnt lgkmcnt(0)
	v_pk_mul_f32 v[2:3], v[2:3], v[12:13]
	s_nop 0
	v_add_f32_e32 v0, v0, v2
	v_add_f32_e32 v0, v0, v3
	v_pk_mul_f32 v[2:3], v[4:5], v[14:15]
	s_nop 0
	v_add_f32_e32 v0, v0, v2
	v_add_f32_e32 v0, v0, v3
	v_min_f32_e32 v2, 0, v0
	v_mul_f32_e64 v0, |v0|, s8
	v_exp_f32_e32 v0, v0
	s_nop 0
	v_add_f32_e32 v0, 1.0, v0
	v_cmp_gt_f32_e32 vcc, s5, v0
	s_nop 1
	v_cndmask_b32_e64 v3, 0, 32, vcc
	v_ldexp_f32 v0, v0, v3
	v_log_f32_e32 v0, v0
	s_nop 0
	v_mul_f32_e32 v3, 0x3f317217, v0
	v_fma_f32 v3, v0, s51, -v3
	v_fmac_f32_e32 v3, 0x3377d1cf, v0
	v_fmac_f32_e32 v3, 0x3f317217, v0
	v_cmp_lt_f32_e64 s[12:13], |v0|, s53
	s_nop 1
	v_cndmask_b32_e64 v0, v0, v3, s[12:13]
	v_cndmask_b32_e32 v3, 0, v44, vcc
	v_sub_f32_e32 v0, v0, v3
	v_sub_f32_e32 v0, v2, v0
	v_fmamk_f32 v9, v0, 0x3d800000, v39
	v_add_u32_e32 v0, 0, v7
	ds_write_b32 v6, v9 offset:51200
	s_waitcnt lgkmcnt(0)
	s_barrier
	ds_read2st64_b32 v[2:3], v0 offset0:200 offset1:202
	v_cmp_lt_i32_e32 vcc, 0, v17
	s_waitcnt lgkmcnt(0)
	v_add_f32_e32 v2, 0, v2
	v_cndmask_b32_e32 v4, 0, v2, vcc
	v_add_f32_e32 v5, v2, v3
	v_cmp_lt_i32_e32 vcc, 1, v17
	v_add_f32_e32 v2, v3, v4
	s_nop 0
	v_cndmask_b32_e32 v4, v4, v2, vcc
	ds_read2st64_b32 v[2:3], v0 offset0:204 offset1:206
	v_cmp_lt_i32_e32 vcc, 2, v17
	s_waitcnt lgkmcnt(0)
	v_add_f32_e32 v0, v5, v2
	v_add_f32_e32 v2, v2, v4
	v_cndmask_b32_e32 v2, v4, v2, vcc
	v_add_f32_e32 v18, v0, v3
	v_cmp_lt_i32_e32 vcc, 3, v17
	v_add_f32_e32 v0, v3, v2
	s_nop 0
	v_cndmask_b32_e32 v0, v2, v0, vcc
	v_lshlrev_b32_e32 v2, 4, v17
	v_ashrrev_i32_e32 v3, 31, v2
	v_lshl_add_u64 v[2:3], s[6:7], 0, v[2:3]
	v_lshlrev_b64 v[2:3], 13, v[2:3]
	v_lshl_add_u64 v[2:3], s[18:19], 0, v[2:3]
	v_sub_f32_e32 v15, v18, v0
	v_lshl_add_u64 v[2:3], v[2:3], 0, s[86:87]
	v_lshlrev_b32_e32 v0, 1, v11
	v_lshl_add_u64 v[12:13], v[2:3], 0, v[0:1]
	v_sub_f32_e32 v0, v15, v22
	v_mul_f32_e32 v0, 0x3fb8aa3b, v0
	v_exp_f32_e32 v2, v0
	v_sub_f32_e32 v0, v15, v26
	v_add_co_u32_e32 v4, vcc, s37, v12
	v_mul_f32_e32 v0, 0x3fb8aa3b, v0
	s_nop 0
	v_addc_co_u32_e32 v5, vcc, 0, v13, vcc
	v_exp_f32_e32 v3, v0
	global_load_ushort v0, v[4:5], off offset:2688
	s_nop 0
	global_load_ushort v4, v[12:13], off offset:2688
	v_add_co_u32_e32 v6, vcc, s79, v12
	s_waitcnt vmcnt(1)
	v_lshlrev_b32_e32 v5, 16, v0
	v_sub_f32_e32 v0, v15, v27
	s_waitcnt vmcnt(0)
	v_lshlrev_b32_e32 v4, 16, v4
	v_mul_f32_e32 v0, 0x3fb8aa3b, v0
	v_pk_mul_f32 v[2:3], v[2:3], v[4:5]
	v_exp_f32_e32 v4, v0
	v_sub_f32_e32 v0, v15, v28
	v_mul_f32_e32 v0, 0x3fb8aa3b, v0
	v_addc_co_u32_e32 v7, vcc, 0, v13, vcc
	v_exp_f32_e32 v5, v0
	global_load_ushort v0, v[6:7], off offset:2688
	v_add_co_u32_e32 v6, vcc, s57, v12
	v_cvt_pk_bf16_f32 v2, v2, v3
	s_nop 0
	v_addc_co_u32_e32 v7, vcc, 0, v13, vcc
	global_load_ushort v3, v[6:7], off offset:2688
	s_waitcnt vmcnt(1)
	v_lshlrev_b32_e32 v6, 16, v0
	v_sub_f32_e32 v0, v15, v29
	v_mul_f32_e32 v0, 0x3fb8aa3b, v0
	s_waitcnt vmcnt(0)
	v_lshlrev_b32_e32 v7, 16, v3
	v_pk_mul_f32 v[4:5], v[4:5], v[6:7]
	v_add_co_u32_e32 v6, vcc, s0, v12
	v_cvt_pk_bf16_f32 v3, v4, v5
	v_exp_f32_e32 v4, v0
	v_sub_f32_e32 v0, v15, v30
	v_mul_f32_e32 v0, 0x3fb8aa3b, v0
	v_addc_co_u32_e32 v7, vcc, 0, v13, vcc
	s_mov_b32 s0, 0xa000
	v_exp_f32_e32 v5, v0
	global_load_ushort v0, v[6:7], off offset:2688
	v_add_co_u32_e32 v6, vcc, s0, v12
	s_mov_b32 s0, 0xe000
	s_nop 0
	v_addc_co_u32_e32 v7, vcc, 0, v13, vcc
	global_load_ushort v6, v[6:7], off offset:2688
	v_add_co_u32_e32 v20, vcc, s48, v12
	s_waitcnt vmcnt(0)
	v_lshlrev_b32_e32 v7, 16, v6
	v_lshlrev_b32_e32 v6, 16, v0
	v_sub_f32_e32 v0, v15, v31
	v_mul_f32_e32 v0, 0x3fb8aa3b, v0
	v_pk_mul_f32 v[4:5], v[4:5], v[6:7]
	v_exp_f32_e32 v6, v0
	v_sub_f32_e32 v0, v15, v32
	v_mul_f32_e32 v0, 0x3fb8aa3b, v0
	v_addc_co_u32_e32 v21, vcc, 0, v13, vcc
	v_exp_f32_e32 v7, v0
	global_load_ushort v0, v[20:21], off offset:2688
	v_add_co_u32_e32 v20, vcc, s0, v12
	v_cvt_pk_bf16_f32 v4, v4, v5
	s_nop 0
	v_addc_co_u32_e32 v21, vcc, 0, v13, vcc
	global_load_ushort v5, v[20:21], off offset:2688
	s_mov_b32 s0, 0x10000
	s_waitcnt vmcnt(1)
	v_lshlrev_b32_e32 v20, 16, v0
	v_sub_f32_e32 v0, v15, v33
	v_mul_f32_e32 v0, 0x3fb8aa3b, v0
	s_waitcnt vmcnt(0)
	v_lshlrev_b32_e32 v21, 16, v5
	v_pk_mul_f32 v[6:7], v[6:7], v[20:21]
	v_add_co_u32_e32 v20, vcc, s0, v12
	v_cvt_pk_bf16_f32 v5, v6, v7
	v_exp_f32_e32 v6, v0
	v_sub_f32_e32 v0, v15, v34
	v_mul_f32_e32 v0, 0x3fb8aa3b, v0
	v_addc_co_u32_e32 v21, vcc, 0, v13, vcc
	v_exp_f32_e32 v7, v0
	global_load_ushort v0, v[20:21], off offset:2688
	v_add_co_u32_e32 v20, vcc, s58, v12
	s_mov_b32 s0, 0x14000
	s_nop 0
	v_addc_co_u32_e32 v21, vcc, 0, v13, vcc
	global_load_ushort v8, v[20:21], off offset:2688
	v_add_co_u32_e32 v22, vcc, s0, v12
	s_mov_b32 s0, 0x1a000
	s_nop 0
	v_addc_co_u32_e32 v23, vcc, 0, v13, vcc
	s_waitcnt vmcnt(1)
	v_lshlrev_b32_e32 v20, 16, v0
	v_sub_f32_e32 v0, v15, v35
	v_mul_f32_e32 v0, 0x3fb8aa3b, v0
	s_waitcnt vmcnt(0)
	v_lshlrev_b32_e32 v21, 16, v8
	v_pk_mul_f32 v[6:7], v[6:7], v[20:21]
	v_exp_f32_e32 v20, v0
	v_sub_f32_e32 v0, v15, v36
	v_mul_f32_e32 v0, 0x3fb8aa3b, v0
	v_exp_f32_e32 v21, v0
	global_load_ushort v0, v[22:23], off offset:2688
	v_add_co_u32_e32 v22, vcc, s36, v12
	v_cvt_pk_bf16_f32 v6, v6, v7
	s_nop 0
	v_addc_co_u32_e32 v23, vcc, 0, v13, vcc
	global_load_ushort v7, v[22:23], off offset:2688
	s_waitcnt vmcnt(1)
	v_lshlrev_b32_e32 v22, 16, v0
	v_sub_f32_e32 v0, v15, v37
	v_mul_f32_e32 v0, 0x3fb8aa3b, v0
	s_waitcnt vmcnt(0)
	v_lshlrev_b32_e32 v23, 16, v7
	v_pk_mul_f32 v[20:21], v[20:21], v[22:23]
	v_add_co_u32_e32 v22, vcc, s52, v12
	v_cvt_pk_bf16_f32 v7, v20, v21
	v_exp_f32_e32 v20, v0
	v_sub_f32_e32 v0, v15, v38
	v_mul_f32_e32 v0, 0x3fb8aa3b, v0
	v_addc_co_u32_e32 v23, vcc, 0, v13, vcc
	v_exp_f32_e32 v21, v0
	global_load_ushort v0, v[22:23], off offset:2688
	v_add_co_u32_e32 v22, vcc, s0, v12
	s_mov_b32 s0, 0x1c000
	s_nop 0
	v_addc_co_u32_e32 v23, vcc, 0, v13, vcc
	global_load_ushort v8, v[22:23], off offset:2688
	s_waitcnt vmcnt(1)
	v_lshlrev_b32_e32 v22, 16, v0
	v_sub_f32_e32 v0, v15, v39
	v_mul_f32_e32 v0, 0x3fb8aa3b, v0
	v_exp_f32_e32 v14, v0
	v_sub_f32_e32 v0, v15, v9
	v_mul_f32_e32 v0, 0x3fb8aa3b, v0
	s_waitcnt vmcnt(0)
	v_lshlrev_b32_e32 v23, 16, v8
	v_pk_mul_f32 v[20:21], v[20:21], v[22:23]
	v_exp_f32_e32 v15, v0
	v_cvt_pk_bf16_f32 v8, v20, v21
	v_add_co_u32_e32 v20, vcc, s0, v12
	s_movk_i32 s0, 0x80
	s_nop 0
	v_addc_co_u32_e32 v21, vcc, 0, v13, vcc
	v_add_co_u32_e32 v12, vcc, s59, v12
	global_load_ushort v0, v[20:21], off offset:2688
	s_nop 0
	v_addc_co_u32_e32 v13, vcc, 0, v13, vcc
	global_load_ushort v9, v[12:13], off offset:2688
	v_cmp_gt_u32_e32 vcc, s0, v10
	s_waitcnt vmcnt(1)
	v_lshlrev_b32_e32 v12, 16, v0
	v_mul_u32_u24_e32 v0, 0x90, v11
	v_lshlrev_b32_e32 v11, 5, v17
	s_waitcnt vmcnt(0)
	v_lshlrev_b32_e32 v13, 16, v9
	v_pk_mul_f32 v[12:13], v[14:15], v[12:13]
	v_add3_u32 v0, 0, v0, v11
	v_cvt_pk_bf16_f32 v9, v12, v13
	ds_write_b128 v0, v[2:5] offset:32768
	ds_write_b128 v0, v[6:9] offset:32784
	s_and_saveexec_b64 s[6:7], vcc
	s_cbranch_execz .LBB0_388
	v_mul_f32_e32 v0, 0x3fb8aa3b, v18
	v_exp_f32_e32 v0, v0
	v_mov_b32_e32 v11, v1
	v_lshl_add_u64 v[2:3], v[10:11], 2, s[26:27]
	global_store_dword v[2:3], v0, off
	s_branch .LBB0_388
